# scan-chain step: next-chunk global prefetch block issued behind the LDS fragment prefetch (on v60)
# speedup vs baseline: 1.0022x; 1.0022x over previous
; DI void dn_scan_chain(CParams& p, int it, int S, char* lds) {
;     ...
;   auto prefetch = [&](int cc_) {
;     const int ch_ = dir ? (NC - 1 - cc_) : cc_;
;     const int tp = tid0 + opq();
;     const bf16_t* uw = UWg + (size_t)ch_ * 8192;
;     const bf16_t* qk = QKg + (size_t)ch_ * 8192;
; #pragma unroll
;     for (int k = 0; k < 2; ++k) {
;       const int ci = tp + 256 * k, row = ci >> 3, c8 = ci & 7;
;       const int srow = dir ? 63 - row : row;
;       ru[k] = *(const u32x4*)(uw + row * 64 + c8 * 8);
;       rw[k] = *(const u32x4*)(uw + 4096 + row * 64 + c8 * 8);
;     ...
;       f32x4 QK[4];
; #pragma unroll
;       for (int t = 0; t < 4; ++t) QK[t] = f32x4{0.f, 0.f, 0.f, 0.f};
; #pragma unroll
;       for (int ks = 0; ks < 2; ++ks) {
;         const bf16x8 bfk = *(const bf16x8*)(Kimg + (16 * w + l15) * 72 + 32 * ks + 8 * g4);
; #pragma unroll
;         for (int rt = 0; rt < 4; ++rt) {
;           const bf16x8 afq = *(const bf16x8*)(Qimg + (16 * rt + l15) * 72 + 32 * ks + 8 * g4);
;           QK[rt] = MFMA16(afq, bfk, QK[rt]);
;         }
;       }
;       const float gcj = gcs[e_col];
; #pragma unroll
;       for (int rt = 0; rt < 4; ++rt)
; #pragma unroll
;         for (int r = 0; r < 4; ++r) {
;           const int i = 16 * rt + 4 * g4 + r;
;           const float ee = __expf(fminf(gcs[i] - gcj, 0.f));
;           Iimg[i * 72 + e_col] = f2bf((i >= e_col) ? QK[rt][r] * ee : 0.f);
;         }
;     }
;     __syncthreads();
;     {
;       bf16x8 Bs[2];
; #pragma unroll
;       for (int ks = 0; ks < 2; ++ks)
;         Bs[ks] = pack8(Sd[2 * ks][0], Sd[2 * ks][1], Sd[2 * ks][2], Sd[2 * ks][3], Sd[2 * ks + 1][0], Sd[2 * ks + 1][1],
;                        Sd[2 * ks + 1][2], Sd[2 * ks + 1][3]);
;       f32x4 vn[4], qs[4], iv[4];
; #pragma unroll
;       for (int rt = 0; rt < 4; ++rt) {
; #pragma unroll
;         for (int r = 0; r < 4; ++r) vn[rt][r] = bf2f(Uimg[(16 * rt + 4 * g4 + r) * 72 + e_col]);
;         qs[rt] = f32x4{0.f, 0.f, 0.f, 0.f};
;         iv[rt] = f32x4{0.f, 0.f, 0.f, 0.f};
; #pragma unroll
;         for (int ks = 0; ks < 2; ++ks) {
;           const bf16_t* wp = Wn + (16 * rt + l15) * 72 + 32 * ks + 4 * g4;
;           const bf16_t* qp = Qimg + (16 * rt + l15) * 72 + 32 * ks + 4 * g4;
;           vn[rt] = MFMA16(ld2x4(wp, wp + 16), Bs[ks], vn[rt]);
;           qs[rt] = MFMA16(ld2x4(qp, qp + 16), Bs[ks], qs[rt]);
;         }
;       }
.LBB0_616:
	v_and_b32_e32 v68, 15, v52
	v_bfe_u32 v69, v52, 4, 2
	v_lshlrev_b32_e32 v54, 4, v69
	v_mul_u32_u24_e32 v70, 0x90, v68
	v_ashrrev_i32_e32 v0, 2, v52
	v_add3_u32 v67, 16, v54, v70
	v_bfi_b32 v98, -16, v0, v52
	s_waitcnt lgkmcnt(0)
	s_barrier
	v_lshl_add_u32 v96, v69, 4, 16
	ds_read_b128 v[80:83], v96 offset:55296
	ds_read_b128 v[84:87], v96 offset:55360
	ds_read_b128 v[88:91], v96 offset:55424
	ds_read_b128 v[92:95], v96 offset:55488
	v_mul_lo_u32 v0, v98, s12
	v_add_u32_e32 v0, 16, v0
	v_add_u32_e32 v66, v0, v54
	s_movk_i32 s6, 0xff74
	ds_read_b128 v[162:165], v66 offset:27648
	ds_read_b128 v[130:133], v67 offset:18432
	ds_read_b128 v[138:141], v67 offset:20736
	ds_read_b128 v[146:149], v67 offset:23040
	ds_read_b128 v[154:157], v67 offset:25344
	ds_read_b128 v[166:169], v66 offset:27712
	ds_read_b128 v[134:137], v67 offset:18496
	ds_read_b128 v[142:145], v67 offset:20800
	ds_read_b128 v[150:153], v67 offset:23104
	ds_read_b128 v[158:161], v67 offset:25408
	s_waitcnt lgkmcnt(8)
	v_mfma_f32_16x16x32_bf16 v[62:65], v[130:133], v[162:165], 0
	s_waitcnt lgkmcnt(7)
	v_mfma_f32_16x16x32_bf16 v[58:61], v[138:141], v[162:165], 0
	s_waitcnt lgkmcnt(6)
	v_mfma_f32_16x16x32_bf16 v[54:57], v[146:149], v[162:165], 0
	s_waitcnt lgkmcnt(5)
	v_mfma_f32_16x16x32_bf16 v[50:53], v[154:157], v[162:165], 0
	s_waitcnt lgkmcnt(3)
	v_mfma_f32_16x16x32_bf16 v[62:65], v[134:137], v[166:169], v[62:65]
	s_waitcnt lgkmcnt(2)
	v_mfma_f32_16x16x32_bf16 v[58:61], v[142:145], v[166:169], v[58:61]
	s_waitcnt lgkmcnt(1)
	v_mfma_f32_16x16x32_bf16 v[54:57], v[150:153], v[166:169], v[54:57]
	s_waitcnt lgkmcnt(0)
	v_mfma_f32_16x16x32_bf16 v[50:53], v[158:161], v[166:169], v[50:53]
	v_mad_u64_u32 v[66:67], s[6:7], v98, s6, v[0:1]
	ds_read_b32 v67, v66 offset:55296
	v_lshlrev_b32_e32 v0, 2, v69
	v_cmp_ge_i32_e64 s[44:45], v0, v98
	v_mov_b32_e32 v72, 0
	v_lshl_add_u32 v71, v0, 2, 16
	v_mov_b32_e32 v73, 0
	v_lshlrev_b32_e32 v126, 3, v69
	v_add3_u32 v126, 16, v126, v70
	v_mul_u32_u24_e32 v127, 0x240, v69
	v_lshl_add_u32 v128, v98, 1, 16
	v_add_u32_e32 v127, v127, v128
	ds_read_b64 v[130:131], v126 offset:9216
	ds_read_b64 v[132:133], v126 offset:9248
	ds_read_b64 v[138:139], v126 offset:18432
	ds_read_b64 v[140:141], v126 offset:18464
	ds_read_b64 v[134:135], v126 offset:9280
	ds_read_b64 v[136:137], v126 offset:9312
	ds_read_b64 v[142:143], v126 offset:18496
	ds_read_b64 v[144:145], v126 offset:18528
	ds_read_b64 v[146:147], v126 offset:11520
	ds_read_b64 v[148:149], v126 offset:11552
	ds_read_b64 v[154:155], v126 offset:20736
	ds_read_b64 v[156:157], v126 offset:20768
	ds_read_b64 v[150:151], v126 offset:11584
	ds_read_b64 v[152:153], v126 offset:11616
	ds_read_b64 v[158:159], v126 offset:20800
	ds_read_b64 v[160:161], v126 offset:20832
	ds_read_b64 v[162:163], v126 offset:13824
	ds_read_b64 v[164:165], v126 offset:13856
	ds_read_b64 v[170:171], v126 offset:23040
	ds_read_b64 v[172:173], v126 offset:23072
	ds_read_b64 v[166:167], v126 offset:13888
	ds_read_b64 v[168:169], v126 offset:13920
	ds_read_b64 v[174:175], v126 offset:23104
	ds_read_b64 v[176:177], v126 offset:23136
	ds_read_b64 v[178:179], v126 offset:16128
	ds_read_b64 v[180:181], v126 offset:16160
	ds_read_b64 v[186:187], v126 offset:25344
	ds_read_b64 v[188:189], v126 offset:25376
	ds_read_b64 v[182:183], v126 offset:16192
	ds_read_b64 v[184:185], v126 offset:16224
	ds_read_b64 v[190:191], v126 offset:25408
	ds_read_b64 v[192:193], v126 offset:25440
	ds_read_u16 v194, v127 offset:0
	ds_read_u16 v195, v127 offset:144
	ds_read_u16 v196, v127 offset:288
	ds_read_u16 v197, v127 offset:432
	ds_read_u16 v198, v127 offset:2304
	ds_read_u16 v199, v127 offset:2448
	ds_read_u16 v200, v127 offset:2592
	ds_read_u16 v201, v127 offset:2736
	ds_read_u16 v202, v127 offset:4608
	ds_read_u16 v203, v127 offset:4752
	ds_read_u16 v204, v127 offset:4896
	ds_read_u16 v205, v127 offset:5040
	ds_read_u16 v206, v127 offset:6912
	ds_read_u16 v207, v127 offset:7056
	ds_read_u16 v208, v127 offset:7200
	ds_read_u16 v209, v127 offset:7344
	s_cmp_ge_u32 s41, s88
	s_cbranch_scc1 .Lchain_pf_skip
	v_mov_b32_e32 v79, 0
	s_add_i32 s8, s62, -1
	s_and_b64 s[6:7], vcc, exec
	s_cselect_b32 s6, s41, s8
	s_ashr_i32 s7, s6, 31
	s_lshl_b64 s[8:9], s[6:7], 14
	s_add_u32 s100, s58, s8
	v_mov_b32 v78, 0
	s_addc_u32 s101, s59, s9
	v_add_u32_e32 v76, v78, v106
	s_add_u32 s8, s56, s8
	v_lshlrev_b32_e32 v78, 4, v76
	s_addc_u32 s9, s57, s9
	v_and_b32_e32 v78, 0x70, v78
	v_lshl_add_u64 v[18:19], s[100:101], 0, v[78:79]
	v_lshl_add_u64 v[26:27], s[8:9], 0, v[78:79]
	v_ashrrev_i32_e32 v78, 3, v76
	v_sub_u32_e32 v2, 63, v78
	v_cndmask_b32_e32 v10, v2, v78, vcc
	v_lshlrev_b32_e32 v2, 6, v78
	v_add_u32_e32 v78, 0x100, v76
	v_ashrrev_i32_e32 v78, 3, v78
	v_sub_u32_e32 v22, 63, v78
	v_cndmask_b32_e32 v30, v22, v78, vcc
	v_lshlrev_b32_e32 v10, 6, v10
	v_lshlrev_b32_e32 v22, 6, v78
	v_lshlrev_b32_e32 v30, 6, v30
	v_ashrrev_i32_e32 v3, 31, v2
	v_ashrrev_i32_e32 v11, 31, v10
	v_ashrrev_i32_e32 v23, 31, v22
	v_ashrrev_i32_e32 v31, 31, v30
	v_lshl_add_u64 v[20:21], v[18:19], 0, s[30:31]
	v_lshl_add_u64 v[28:29], v[26:27], 0, s[30:31]
	v_lshlrev_b64 v[2:3], 1, v[2:3]
	v_lshlrev_b64 v[10:11], 1, v[10:11]
	v_lshlrev_b64 v[22:23], 1, v[22:23]
	v_lshlrev_b64 v[30:31], 1, v[30:31]
	v_lshl_add_u64 v[4:5], v[18:19], 0, v[2:3]
	v_lshl_add_u64 v[6:7], v[20:21], 0, v[2:3]
	v_lshl_add_u64 v[12:13], v[26:27], 0, v[10:11]
	v_lshl_add_u64 v[14:15], v[28:29], 0, v[10:11]
	v_lshl_add_u64 v[18:19], v[18:19], 0, v[22:23]
	v_lshl_add_u64 v[22:23], v[20:21], 0, v[22:23]
	v_lshl_add_u64 v[26:27], v[26:27], 0, v[30:31]
	v_lshl_add_u64 v[30:31], v[28:29], 0, v[30:31]
	global_load_dwordx4 v[2:5], v[4:5], off
	global_load_dwordx4 v[6:9], v[6:7], off
	global_load_dwordx4 v[10:13], v[12:13], off
	global_load_dwordx4 v[14:17], v[14:15], off
	global_load_dwordx4 v[18:21], v[18:19], off
	global_load_dwordx4 v[22:25], v[22:23], off
	global_load_dwordx4 v[26:29], v[26:27], off
	global_load_dwordx4 v[30:33], v[30:31], off
	v_cmp_gt_i32_e64 s[100:101], 64, v76
	s_and_saveexec_b64 s[8:9], s[100:101]
	s_cbranch_execz .LBB0_615
	s_lshl_b64 s[6:7], s[6:7], 8
	s_add_u32 s6, s60, s6
	s_addc_u32 s7, s61, s7
	v_ashrrev_i32_e32 v77, 31, v76
	v_lshl_add_u64 v[76:77], v[76:77], 2, s[6:7]
	global_load_dword v107, v[76:77], off

; DI void dn_scan_chain(CParams& p, int it, int S, char* lds) {
;     ...
;       const float gcj = gcs[e_col];
; #pragma unroll
;       for (int rt = 0; rt < 4; ++rt)
; #pragma unroll
;         for (int r = 0; r < 4; ++r) {
;           const int i = 16 * rt + 4 * g4 + r;
;           const float ee = __expf(fminf(gcs[i] - gcj, 0.f));
;           Iimg[i * 72 + e_col] = f2bf((i >= e_col) ? QK[rt][r] * ee : 0.f);
.Lchain_pf_skip:
	s_waitcnt lgkmcnt(0)
	s_and_saveexec_b64 s[6:7], s[44:45]
	s_cbranch_execz .LBB0_618
	v_sub_f32_e32 v73, v80, v67
	v_min_f32_e32 v73, 0, v73
	v_mul_f32_e32 v73, 0x3fb8aa3b, v73
	v_exp_f32_e32 v73, v73
	s_nop 0
	v_mul_f32_e32 v62, v62, v73
	v_cvt_pk_bf16_f32 v73, v62, s0
